# attention: first 8 V transpose reads of each PV issued before the trailing permlane swaps of the softmax finish (on top of fast-path tail)
# speedup vs baseline: 1.0044x; 1.0044x over previous
; __device__ __forceinline__ void finishSM(f32x16& p0, f32x16& p1, float alpha, float& l_reg, bf16x8& pa0, bf16x8& pa1, bf16x8& pa2, bf16x8& pa3) {
; #pragma unroll
;     for (int r = 0; r < 16; ++r) p1[r] = __builtin_amdgcn_exp2f(p1[r]);
;     float ps = 0;
; #pragma unroll
;     for (int r = 0; r < 16; ++r) ps += p0[r];
; #pragma unroll
;     for (int r = 0; r < 16; ++r) ps += p1[r];
;     { auto rr = __builtin_amdgcn_permlane32_swap(__float_as_uint(ps), __float_as_uint(ps), false, false);
;       ps = __uint_as_float(rr[0]) + __uint_as_float(rr[1]); }
;     l_reg = l_reg * alpha + ps;
;     ...
;     PK4(p0, 0, pa0); PK4(p0, 8, pa1); PK4(p1, 0, pa2); PK4(p1, 8, pa3);
;     ...
; }
; __device__ __forceinline__ void qkt(f32x16& p0, f32x16& p1, const char* Kn, const bf16x8* qr, int r32, int hi) {
;     const char* Kr = Kn + KR_OFF;
;     p0 = f32x16{}; p1 = f32x16{};
;     __builtin_amdgcn_s_setprio(1);
; #pragma unroll
;     for (int d0 = 0; d0 < 8; ++d0) { const int cb = (d0 * 16 + hi * 8) * 2;
;         const bf16x8 b0 = *reinterpret_cast<const bf16x8*>(Kn + KNSWZ(r32, cb));
;         const bf16x8 b1 = *reinterpret_cast<const bf16x8*>(Kn + KNSWZ(32 + r32, cb));
;         p0 = __builtin_amdgcn_mfma_f32_32x32x16_bf16(b0, qr[d0], p0, 0, 0, 0);
;         p1 = __builtin_amdgcn_mfma_f32_32x32x16_bf16(b1, qr[d0], p1, 0, 0, 0); }
; #pragma unroll
;     for (int d0 = 0; d0 < 4; ++d0) { const int cb = (d0 * 16 + hi * 8) * 2;
;         const bf16x8 b0 = *reinterpret_cast<const bf16x8*>(Kr + KRSWZ(r32, cb));
;         const bf16x8 b1 = *reinterpret_cast<const bf16x8*>(Kr + KRSWZ(32 + r32, cb));
;         p0 = __builtin_amdgcn_mfma_f32_32x32x16_bf16(b0, qr[8 + d0], p0, 0, 0, 0);
;         p1 = __builtin_amdgcn_mfma_f32_32x32x16_bf16(b1, qr[8 + d0], p1, 0, 0, 0); }
; }
; __device__ __forceinline__ int v_st(int k, int c) { const int kk = (k & ~0xC) | ((k & 4) << 1) | ((k & 8) >> 1); return ((kk >> 3) * 4 + (c >> 5)) * 512 + ((kk & 7) * 32 + (c & 31)) * 2; }
; __device__ __forceinline__ int v_rd_base(int lane) { return ((lane & 3) << 3) | (((lane >> 2) & 3) << 6) | (((lane >> 4) & 1) << 5) | (((lane >> 5) & 1) << 8); }
; template <int OFF> __device__ __forceinline__ s16x4 tr_read(int vb) {
;     s16x4 r; asm volatile("ds_read_b64_tr_b16 %0, %1 offset:%2" : "=&v"(r) : "v"(vb), "i"(OFF) : "memory"); return r;
; }
.LBB0_216:
	s_mul_i32 s0, s9, 0x6000
	s_add_i32 s14, s0, 0
	s_lshl_b32 s13, s9, 14
	s_add_i32 s16, s14, s6
	s_add_i32 s17, s7, s13
	s_add_i32 s18, s14, s8
	s_mov_b32 s13, s10
	s_mov_b32 s10, s15
	s_mul_i32 s0, s13, 0x6000
	s_add_i32 s0, s0, 0
	s_setprio 1
	v_add_u32_e32 v84, s0, v207
	ds_read_b128 v[80:83], v84
	ds_read_b128 v[84:87], v84 offset:8192
	v_add_u32_e32 v168, s0, v210
	ds_read_b128 v[196:199], v168
	ds_read_b128 v[168:171], v168 offset:8192
	v_add_u32_e32 v184, s0, v218
	s_waitcnt lgkmcnt(0)
	v_mfma_f32_32x32x16_bf16 v[96:111], v[80:83], v[156:159], 0
	v_mfma_f32_32x32x16_bf16 v[80:95], v[84:87], v[156:159], 0
	v_mfma_f32_32x32x16_bf16 v[96:111], v[196:199], v[152:155], v[96:111]
	v_mfma_f32_32x32x16_bf16 v[80:95], v[168:171], v[152:155], v[80:95]
	ds_read_b128 v[168:171], v184
	ds_read_b128 v[196:199], v184 offset:8192
	v_add_u32_e32 v184, s0, v221
	s_mov_b32 m0, s16
	s_add_u32 s100, s72, 0x26500000
	s_addc_u32 s101, s73, 0
	global_load_lds_dwordx4 v178, s[100:101]
	s_waitcnt lgkmcnt(0)
	v_mfma_f32_32x32x16_bf16 v[96:111], v[168:171], v[148:151], v[96:111]
	v_mfma_f32_32x32x16_bf16 v[80:95], v[196:199], v[148:151], v[80:95]
	ds_read_b128 v[168:171], v184
	ds_read_b128 v[196:199], v184 offset:8192
	v_add_u32_e32 v184, s0, v222
	s_waitcnt lgkmcnt(0)
	v_mfma_f32_32x32x16_bf16 v[96:111], v[168:171], v[144:147], v[96:111]
	v_mfma_f32_32x32x16_bf16 v[80:95], v[196:199], v[144:147], v[80:95]
	ds_read_b128 v[168:171], v184
	ds_read_b128 v[196:199], v184 offset:8192
	v_add_u32_e32 v184, s0, v223
	s_add_i32 m0, s16, 0x400
	s_nop 0
	global_load_lds_dwordx4 v180, s[100:101]
	s_waitcnt lgkmcnt(0)
	v_mfma_f32_32x32x16_bf16 v[96:111], v[168:171], v[140:143], v[96:111]
	v_mfma_f32_32x32x16_bf16 v[80:95], v[196:199], v[140:143], v[80:95]
	ds_read_b128 v[168:171], v184
	ds_read_b128 v[196:199], v184 offset:8192
	v_add_u32_e32 v184, s0, v224
	v_exp_f32_e32 v233, v73
	s_waitcnt lgkmcnt(0)
	v_mfma_f32_32x32x16_bf16 v[96:111], v[168:171], v[136:139], v[96:111]
	v_mfma_f32_32x32x16_bf16 v[80:95], v[196:199], v[136:139], v[80:95]
	ds_read_b128 v[168:171], v184
	ds_read_b128 v[196:199], v184 offset:8192
	v_add_u32_e32 v184, s0, v225
	s_mov_b32 m0, s17
	s_add_u32 s100, s72, 0x26500100
	s_addc_u32 s101, s73, 0
	global_load_lds_dwordx4 v176, s[100:101]
	v_exp_f32_e32 v250, v74
	s_waitcnt lgkmcnt(0)
	v_mfma_f32_32x32x16_bf16 v[96:111], v[168:171], v[132:135], v[96:111]
	v_mfma_f32_32x32x16_bf16 v[80:95], v[196:199], v[132:135], v[80:95]
	ds_read_b128 v[168:171], v184
	ds_read_b128 v[196:199], v184 offset:8192
	v_add_u32_e32 v184, s0, v226
	v_exp_f32_e32 v200, v75
	s_waitcnt lgkmcnt(0)
	v_mfma_f32_32x32x16_bf16 v[96:111], v[168:171], v[128:131], v[96:111]
	v_mfma_f32_32x32x16_bf16 v[80:95], v[196:199], v[128:131], v[80:95]
	ds_read_b128 v[168:171], v184 offset:16384
	ds_read_b128 v[196:199], v184 offset:20480
	v_add_u32_e32 v184, s0, v227
	s_add_i32 m0, s17, 0x400
	s_add_u32 s100, s72, 0x26500180
	s_addc_u32 s101, s73, 0
	global_load_lds_dwordx4 v176, s[100:101]
	v_exp_f32_e32 v195, v76
	s_waitcnt lgkmcnt(0)
	v_mfma_f32_32x32x16_bf16 v[96:111], v[168:171], v[124:127], v[96:111]
	v_mfma_f32_32x32x16_bf16 v[80:95], v[196:199], v[124:127], v[80:95]
	ds_read_b128 v[168:171], v184 offset:16384
	ds_read_b128 v[196:199], v184 offset:20480
	v_add_u32_e32 v184, s0, v228
	v_exp_f32_e32 v172, v77
	s_waitcnt lgkmcnt(0)
	v_mfma_f32_32x32x16_bf16 v[96:111], v[168:171], v[120:123], v[96:111]
	v_mfma_f32_32x32x16_bf16 v[80:95], v[196:199], v[120:123], v[80:95]
	ds_read_b128 v[168:171], v184 offset:16384
	ds_read_b128 v[196:199], v184 offset:20480
	v_add_u32_e32 v184, s0, v229
	s_add_i32 m0, s18, 0x4000
	s_add_u32 s100, s72, 0x21204000
	s_addc_u32 s101, s73, 0
	global_load_lds_dwordx4 v174, s[100:101]
	v_exp_f32_e32 v173, v78
	s_waitcnt lgkmcnt(0)
	v_mfma_f32_32x32x16_bf16 v[96:111], v[168:171], v[116:119], v[96:111]
	v_mfma_f32_32x32x16_bf16 v[80:95], v[196:199], v[116:119], v[80:95]
	ds_read_b128 v[168:171], v184 offset:16384
	ds_read_b128 v[196:199], v184 offset:20480
	v_exp_f32_e32 v184, v68
	v_exp_f32_e32 v79, v79
	s_waitcnt lgkmcnt(0)
	v_mfma_f32_32x32x16_bf16 v[96:111], v[168:171], v[112:115], v[96:111]
	v_exp_f32_e32 v168, v64
	v_add_f32_e32 v64, 0, v247
	v_add_f32_e32 v64, v249, v64
	v_add_f32_e32 v64, v245, v64
	v_add_f32_e32 v64, v248, v64
	v_add_f32_e32 v64, v244, v64
	v_add_f32_e32 v64, v246, v64
	v_add_f32_e32 v64, v242, v64
	v_add_f32_e32 v64, v243, v64
	v_add_f32_e32 v64, v239, v64
	v_add_f32_e32 v64, v241, v64
	v_add_f32_e32 v64, v238, v64
	v_add_f32_e32 v64, v240, v64
	v_add_f32_e32 v64, v235, v64
	v_exp_f32_e32 v169, v65
	v_add_f32_e32 v64, v237, v64
	v_exp_f32_e32 v170, v66
	v_add_f32_e32 v64, v234, v64
	v_exp_f32_e32 v171, v67
	v_add_f32_e32 v64, v236, v64
	v_add_f32_e32 v64, v168, v64
	v_mfma_f32_32x32x16_bf16 v[80:95], v[196:199], v[112:115], v[80:95]
	v_exp_f32_e32 v196, v69
	v_add_f32_e32 v64, v169, v64
	v_exp_f32_e32 v197, v70
	v_add_f32_e32 v64, v170, v64
	v_exp_f32_e32 v198, v71
	v_add_f32_e32 v64, v171, v64
	v_exp_f32_e32 v199, v72
	v_add_f32_e32 v64, v184, v64
	v_add_f32_e32 v64, v196, v64
	v_add_f32_e32 v64, v197, v64
	v_add_f32_e32 v64, v198, v64
	v_add_f32_e32 v64, v199, v64
	v_add_f32_e32 v64, v233, v64
	v_add_f32_e32 v64, v250, v64
	v_add_f32_e32 v64, v200, v64
	v_add_f32_e32 v64, v195, v64
	v_add_f32_e32 v64, v172, v64
	v_add_f32_e32 v64, v173, v64
	v_add_f32_e32 v231, v79, v64
	v_mov_b32_e32 v232, v231
	v_cvt_pk_bf16_f32 v64, v247, v249
	v_cvt_pk_bf16_f32 v65, v245, v248
	v_cvt_pk_bf16_f32 v66, v244, v246
	s_nop 1
	v_permlane32_swap_b32_e32 v231, v232
	v_cvt_pk_bf16_f32 v67, v242, v243
	v_permlane32_swap_b32_e32 v64, v66
	v_cvt_pk_bf16_f32 v68, v239, v241
	v_cvt_pk_bf16_f32 v69, v238, v240
	v_cvt_pk_bf16_f32 v70, v235, v237
	v_cvt_pk_bf16_f32 v71, v234, v236
	v_cvt_pk_bf16_f32 v72, v168, v169
	v_cvt_pk_bf16_f32 v73, v170, v171
	v_cvt_pk_bf16_f32 v74, v184, v196
	v_cvt_pk_bf16_f32 v75, v197, v198
	v_cvt_pk_bf16_f32 v76, v199, v233
	v_cvt_pk_bf16_f32 v77, v250, v200
	v_cvt_pk_bf16_f32 v78, v195, v172
	v_cvt_pk_bf16_f32 v79, v173, v79
	s_lshl_b32 s15, s15, 14
	v_add_u32_e32 v172, s15, v205
	ds_read_b64_tr_b16 v[168:169], v172 offset:0
	ds_read_b64_tr_b16 v[170:171], v172 offset:0x800
	ds_read_b64_tr_b16 v[196:197], v172 offset:0x1000
	ds_read_b64_tr_b16 v[198:199], v172 offset:0x1800
	ds_read_b64_tr_b16 v[234:235], v172 offset:0x2000
	ds_read_b64_tr_b16 v[236:237], v172 offset:0x2800
	ds_read_b64_tr_b16 v[238:239], v172 offset:0x3000
	ds_read_b64_tr_b16 v[240:241], v172 offset:0x3800
	v_permlane32_swap_b32_e32 v65, v67
	v_permlane32_swap_b32_e32 v68, v70
	v_permlane32_swap_b32_e32 v69, v71
	v_permlane32_swap_b32_e32 v72, v74
	v_permlane32_swap_b32_e32 v73, v75
	v_permlane32_swap_b32_e32 v76, v78
	v_permlane32_swap_b32_e32 v77, v79
	s_setprio 0
	s_waitcnt lgkmcnt(0)
; #define SBAR() __builtin_amdgcn_sched_barrier(0)
; __device__ __forceinline__ void qkt(f32x16& p0, f32x16& p1, const char* Kn, const bf16x8* qr, int r32, int hi) {
;     const char* Kr = Kn + KR_OFF;
;     p0 = f32x16{}; p1 = f32x16{};
;     __builtin_amdgcn_s_setprio(1);
; #pragma unroll
;     for (int d0 = 0; d0 < 8; ++d0) { const int cb = (d0 * 16 + hi * 8) * 2;
;         const bf16x8 b0 = *reinterpret_cast<const bf16x8*>(Kn + KNSWZ(r32, cb));
;         const bf16x8 b1 = *reinterpret_cast<const bf16x8*>(Kn + KNSWZ(32 + r32, cb));
;         p0 = __builtin_amdgcn_mfma_f32_32x32x16_bf16(b0, qr[d0], p0, 0, 0, 0);
;         p1 = __builtin_amdgcn_mfma_f32_32x32x16_bf16(b1, qr[d0], p1, 0, 0, 0); }
; #pragma unroll
;     for (int d0 = 0; d0 < 4; ++d0) { const int cb = (d0 * 16 + hi * 8) * 2;
;         const bf16x8 b0 = *reinterpret_cast<const bf16x8*>(Kr + KRSWZ(r32, cb));
;         const bf16x8 b1 = *reinterpret_cast<const bf16x8*>(Kr + KRSWZ(32 + r32, cb));
;         p0 = __builtin_amdgcn_mfma_f32_32x32x16_bf16(b0, qr[8 + d0], p0, 0, 0, 0);
;         p1 = __builtin_amdgcn_mfma_f32_32x32x16_bf16(b1, qr[8 + d0], p1, 0, 0, 0); }
; }
; __device__ __forceinline__ int v_st(int k, int c) { const int kk = (k & ~0xC) | ((k & 4) << 1) | ((k & 8) >> 1); return ((kk >> 3) * 4 + (c >> 5)) * 512 + ((kk & 7) * 32 + (c & 31)) * 2; }
; __device__ __forceinline__ int v_rd_base(int lane) { return ((lane & 3) << 3) | (((lane >> 2) & 3) << 6) | (((lane >> 4) & 1) << 5) | (((lane >> 5) & 1) << 8); }
; template <int OFF> __device__ __forceinline__ s16x4 tr_read(int vb) {
;     s16x4 r; asm volatile("ds_read_b64_tr_b16 %0, %1 offset:%2" : "=&v"(r) : "v"(vb), "i"(OFF) : "memory"); return r;
; }
; template <int D0> __device__ __forceinline__ void pv_one(f32x16& od, int vb, bf16x8 pa0, bf16x8 pa1, bf16x8 pa2, bf16x8 pa3) {
;     const s16x4 l0 = tr_read<v_rd_off(D0, 0, 0)>(vb), h0 = tr_read<v_rd_off(D0, 0, 1)>(vb), l1 = tr_read<v_rd_off(D0, 1, 0)>(vb), h1 = tr_read<v_rd_off(D0, 1, 1)>(vb);
;     const s16x4 l2 = tr_read<v_rd_off(D0, 2, 0)>(vb), h2 = tr_read<v_rd_off(D0, 2, 1)>(vb), l3 = tr_read<v_rd_off(D0, 3, 0)>(vb), h3 = tr_read<v_rd_off(D0, 3, 1)>(vb);
;     asm volatile("s_waitcnt lgkmcnt(0)" ::: "memory"); SBAR();
;     ...
;     od = __builtin_amdgcn_mfma_f32_32x32x16_bf16(pa0, PK(l0, h0), od, 0, 0, 0);
;     od = __builtin_amdgcn_mfma_f32_32x32x16_bf16(pa1, PK(l1, h1), od, 0, 0, 0);
	s_nop 0
	v_mfma_f32_32x32x16_bf16 v[0:15], v[64:67], v[168:171], v[0:15]
	ds_read_b64_tr_b16 v[168:169], v172 offset:0x200
	ds_read_b64_tr_b16 v[170:171], v172 offset:0xa00
	v_mfma_f32_32x32x16_bf16 v[0:15], v[68:71], v[196:199], v[0:15]
	ds_read_b64_tr_b16 v[196:197], v172 offset:0x1200
	ds_read_b64_tr_b16 v[198:199], v172 offset:0x1a00
	v_mfma_f32_32x32x16_bf16 v[0:15], v[72:75], v[234:237], v[0:15]
	ds_read_b64_tr_b16 v[234:235], v172 offset:0x2200
	ds_read_b64_tr_b16 v[236:237], v172 offset:0x2a00
	v_mfma_f32_32x32x16_bf16 v[0:15], v[76:79], v[238:241], v[0:15]
	ds_read_b64_tr_b16 v[238:239], v172 offset:0x3200
	ds_read_b64_tr_b16 v[240:241], v172 offset:0x3a00
	s_waitcnt lgkmcnt(0)
	v_mfma_f32_32x32x16_bf16 v[48:63], v[64:67], v[168:171], v[48:63]
	ds_read_b64_tr_b16 v[168:169], v172 offset:0x400
	ds_read_b64_tr_b16 v[170:171], v172 offset:0xc00
	v_mfma_f32_32x32x16_bf16 v[48:63], v[68:71], v[196:199], v[48:63]
	ds_read_b64_tr_b16 v[196:197], v172 offset:0x1400
	ds_read_b64_tr_b16 v[198:199], v172 offset:0x1c00
	v_mfma_f32_32x32x16_bf16 v[48:63], v[72:75], v[234:237], v[48:63]
	ds_read_b64_tr_b16 v[234:235], v172 offset:0x2400
	ds_read_b64_tr_b16 v[236:237], v172 offset:0x2c00
	v_mfma_f32_32x32x16_bf16 v[48:63], v[76:79], v[238:241], v[48:63]
	ds_read_b64_tr_b16 v[238:239], v172 offset:0x3400
	ds_read_b64_tr_b16 v[240:241], v172 offset:0x3c00
	s_waitcnt lgkmcnt(0)
	v_mfma_f32_32x32x16_bf16 v[32:47], v[64:67], v[168:171], v[32:47]
	ds_read_b64_tr_b16 v[168:169], v172 offset:0x600
	ds_read_b64_tr_b16 v[170:171], v172 offset:0xe00
	v_mfma_f32_32x32x16_bf16 v[32:47], v[68:71], v[196:199], v[32:47]
	ds_read_b64_tr_b16 v[196:197], v172 offset:0x1600
	ds_read_b64_tr_b16 v[198:199], v172 offset:0x1e00
	v_mfma_f32_32x32x16_bf16 v[32:47], v[72:75], v[234:237], v[32:47]
	ds_read_b64_tr_b16 v[234:235], v172 offset:0x2600
	ds_read_b64_tr_b16 v[236:237], v172 offset:0x2e00
	v_mfma_f32_32x32x16_bf16 v[32:47], v[76:79], v[238:241], v[32:47]
	ds_read_b64_tr_b16 v[238:239], v172 offset:0x3600
	ds_read_b64_tr_b16 v[240:241], v172 offset:0x3e00
	s_waitcnt lgkmcnt(0)
	v_mfma_f32_32x32x16_bf16 v[16:31], v[64:67], v[168:171], v[16:31]
	v_max_f32_e32 v64, v97, v97
	v_max_f32_e32 v65, v96, v96
	v_max_f32_e32 v64, v65, v64
	v_max3_f32 v64, v64, v98, v99
	v_max3_f32 v64, v64, v100, v101
	v_max3_f32 v64, v64, v102, v103
	v_max3_f32 v64, v64, v104, v105
	v_mfma_f32_32x32x16_bf16 v[16:31], v[68:71], v[196:199], v[16:31]
	v_max3_f32 v64, v64, v106, v107
	v_max3_f32 v64, v64, v108, v109
	v_max3_f32 v64, v64, v110, v111
	v_max3_f32 v64, v64, v80, v81
	v_max3_f32 v64, v64, v82, v83
	v_max3_f32 v64, v64, v84, v85
	v_max3_f32 v64, v64, v86, v87
	v_mfma_f32_32x32x16_bf16 v[16:31], v[72:75], v[234:237], v[16:31]
	v_max3_f32 v64, v64, v88, v89
	v_max3_f32 v64, v64, v90, v91
	v_max3_f32 v64, v64, v92, v93
	v_max3_f32 v64, v64, v94, v95
	v_mov_b32_e32 v65, v64
	s_nop 1
	v_permlane32_swap_b32_e32 v64, v65
	v_max_f32_e32 v65, v65, v65
	v_max_f32_e32 v64, v64, v64
	v_mfma_f32_32x32x16_bf16 v[16:31], v[76:79], v[238:241], v[16:31]
	v_max_f32_e32 v64, v64, v65
	v_sub_f32_e32 v65, v64, v182
	s_mov_b32 s0, 0x41300000
	v_cmp_ge_f32_e32 vcc, s0, v65
	v_mov_b32_e32 v184, v182
	v_mov_b32_e32 v233, 1.0
	s_cmp_eq_u64 vcc, exec
	s_cbranch_scc0 .Latt_slow1
	s_cmp_lg_u32 s19, 0
	s_cbranch_scc0 .LBB0_228
.LBB0_221:
	v_exp_f32_e32 v182, v98
	v_exp_f32_e32 v172, v96
	v_exp_f32_e32 v173, v97
	v_exp_f32_e32 v195, v99
	v_exp_f32_e32 v196, v100
	v_exp_f32_e32 v197, v101
	v_exp_f32_e32 v198, v102
	v_exp_f32_e32 v199, v103
	v_exp_f32_e32 v200, v104
	v_exp_f32_e32 v234, v105
	v_exp_f32_e32 v235, v106
	v_exp_f32_e32 v236, v107
	v_exp_f32_e32 v237, v108
	v_exp_f32_e32 v238, v109
	v_exp_f32_e32 v239, v110
	v_exp_f32_e32 v240, v111
	s_mul_i32 s0, s10, 0x6000
	s_add_i32 s16, s0, 0
	s_add_i32 s17, s16, s6
	s_add_i32 s18, s16, s8
	s_waitcnt vmcnt(0) lgkmcnt(0)
	s_barrier
	s_add_i32 s15, s7, s15
	s_setprio 1
	v_add_u32_e32 v68, s14, v207
	ds_read_b128 v[64:67], v68
	ds_read_b128 v[68:71], v68 offset:8192
	v_add_u32_e32 v186, s14, v210
	ds_read_b128 v[168:171], v186
	ds_read_b128 v[186:189], v186 offset:8192
	s_waitcnt lgkmcnt(0)
	v_mfma_f32_32x32x16_bf16 v[96:111], v[64:67], v[156:159], 0
	v_mfma_f32_32x32x16_bf16 v[64:79], v[68:71], v[156:159], 0
	v_mfma_f32_32x32x16_bf16 v[96:111], v[168:171], v[152:155], v[96:111]
	v_mfma_f32_32x32x16_bf16 v[64:79], v[186:189], v[152:155], v[64:79]
	v_add_u32_e32 v186, s14, v218
	ds_read_b128 v[168:171], v186
	ds_read_b128 v[186:189], v186 offset:8192
	s_mov_b32 m0, s17
	s_add_u32 s100, s72, 0x26580000
	s_addc_u32 s101, s73, 0
	global_load_lds_dwordx4 v178, s[100:101]
	s_waitcnt lgkmcnt(0)
	v_mfma_f32_32x32x16_bf16 v[96:111], v[168:171], v[148:151], v[96:111]
	v_mfma_f32_32x32x16_bf16 v[64:79], v[186:189], v[148:151], v[64:79]
	v_add_u32_e32 v186, s14, v221
	ds_read_b128 v[168:171], v186
	ds_read_b128 v[186:189], v186 offset:8192
	s_waitcnt lgkmcnt(0)
	v_mfma_f32_32x32x16_bf16 v[96:111], v[168:171], v[144:147], v[96:111]
	v_mfma_f32_32x32x16_bf16 v[64:79], v[186:189], v[144:147], v[64:79]
	v_add_u32_e32 v186, s14, v222
	ds_read_b128 v[168:171], v186
	ds_read_b128 v[186:189], v186 offset:8192
	s_add_i32 m0, s17, 0x400
	s_nop 0
	global_load_lds_dwordx4 v180, s[100:101]
	v_exp_f32_e32 v190, v88
	s_waitcnt lgkmcnt(0)
	v_mfma_f32_32x32x16_bf16 v[96:111], v[168:171], v[140:143], v[96:111]
	v_mfma_f32_32x32x16_bf16 v[64:79], v[186:189], v[140:143], v[64:79]
	v_add_u32_e32 v186, s14, v223
	ds_read_b128 v[168:171], v186
	ds_read_b128 v[186:189], v186 offset:8192
	v_exp_f32_e32 v191, v89
	s_waitcnt lgkmcnt(0)
; __device__ __forceinline__ void finishSM(f32x16& p0, f32x16& p1, float alpha, float& l_reg, bf16x8& pa0, bf16x8& pa1, bf16x8& pa2, bf16x8& pa3) {
; #pragma unroll
;     for (int r = 0; r < 16; ++r) p1[r] = __builtin_amdgcn_exp2f(p1[r]);
;     float ps = 0;
; #pragma unroll
;     for (int r = 0; r < 16; ++r) ps += p0[r];
; #pragma unroll
;     for (int r = 0; r < 16; ++r) ps += p1[r];
;     { auto rr = __builtin_amdgcn_permlane32_swap(__float_as_uint(ps), __float_as_uint(ps), false, false);
;       ps = __uint_as_float(rr[0]) + __uint_as_float(rr[1]); }
;     l_reg = l_reg * alpha + ps;
;     ...
;     PK4(p0, 0, pa0); PK4(p0, 8, pa1); PK4(p1, 0, pa2); PK4(p1, 8, pa3);
;     ...
; }
; __device__ __forceinline__ void qkt(f32x16& p0, f32x16& p1, const char* Kn, const bf16x8* qr, int r32, int hi) {
;     const char* Kr = Kn + KR_OFF;
;     p0 = f32x16{}; p1 = f32x16{};
;     __builtin_amdgcn_s_setprio(1);
; #pragma unroll
;     for (int d0 = 0; d0 < 8; ++d0) { const int cb = (d0 * 16 + hi * 8) * 2;
;         const bf16x8 b0 = *reinterpret_cast<const bf16x8*>(Kn + KNSWZ(r32, cb));
;         const bf16x8 b1 = *reinterpret_cast<const bf16x8*>(Kn + KNSWZ(32 + r32, cb));
;         p0 = __builtin_amdgcn_mfma_f32_32x32x16_bf16(b0, qr[d0], p0, 0, 0, 0);
;         p1 = __builtin_amdgcn_mfma_f32_32x32x16_bf16(b1, qr[d0], p1, 0, 0, 0); }
; #pragma unroll
;     for (int d0 = 0; d0 < 4; ++d0) { const int cb = (d0 * 16 + hi * 8) * 2;
;         const bf16x8 b0 = *reinterpret_cast<const bf16x8*>(Kr + KRSWZ(r32, cb));
;         const bf16x8 b1 = *reinterpret_cast<const bf16x8*>(Kr + KRSWZ(32 + r32, cb));
;         p0 = __builtin_amdgcn_mfma_f32_32x32x16_bf16(b0, qr[8 + d0], p0, 0, 0, 0);
;         p1 = __builtin_amdgcn_mfma_f32_32x32x16_bf16(b1, qr[8 + d0], p1, 0, 0, 0); }
; }
	v_mfma_f32_32x32x16_bf16 v[96:111], v[168:171], v[136:139], v[96:111]
	v_mfma_f32_32x32x16_bf16 v[64:79], v[186:189], v[136:139], v[64:79]
	v_add_u32_e32 v186, s14, v224
	ds_read_b128 v[168:171], v186
	ds_read_b128 v[186:189], v186 offset:8192
	s_mov_b32 m0, s15
	s_add_u32 s100, s72, 0x26580100
	s_addc_u32 s101, s73, 0
	global_load_lds_dwordx4 v176, s[100:101]
	v_exp_f32_e32 v192, v90
	s_waitcnt lgkmcnt(0)
	v_mfma_f32_32x32x16_bf16 v[96:111], v[168:171], v[132:135], v[96:111]
	v_mfma_f32_32x32x16_bf16 v[64:79], v[186:189], v[132:135], v[64:79]
	v_add_u32_e32 v186, s14, v225
	ds_read_b128 v[168:171], v186
	ds_read_b128 v[186:189], v186 offset:8192
	v_exp_f32_e32 v193, v91
	s_waitcnt lgkmcnt(0)
	v_mfma_f32_32x32x16_bf16 v[96:111], v[168:171], v[128:131], v[96:111]
	v_mfma_f32_32x32x16_bf16 v[64:79], v[186:189], v[128:131], v[64:79]
	v_add_u32_e32 v186, s14, v226
	ds_read_b128 v[168:171], v186 offset:16384
	ds_read_b128 v[186:189], v186 offset:20480
	s_add_i32 m0, s15, 0x400
	s_add_u32 s100, s72, 0x26580180
	s_addc_u32 s101, s73, 0
	global_load_lds_dwordx4 v176, s[100:101]
	v_exp_f32_e32 v241, v92
	s_waitcnt lgkmcnt(0)
	v_mfma_f32_32x32x16_bf16 v[96:111], v[168:171], v[124:127], v[96:111]
	v_mfma_f32_32x32x16_bf16 v[64:79], v[186:189], v[124:127], v[64:79]
	v_add_u32_e32 v186, s14, v227
	ds_read_b128 v[168:171], v186 offset:16384
	ds_read_b128 v[186:189], v186 offset:20480
	v_exp_f32_e32 v242, v93
	s_waitcnt lgkmcnt(0)
	v_mfma_f32_32x32x16_bf16 v[96:111], v[168:171], v[120:123], v[96:111]
	v_mfma_f32_32x32x16_bf16 v[64:79], v[186:189], v[120:123], v[64:79]
	v_add_u32_e32 v186, s14, v228
	ds_read_b128 v[168:171], v186 offset:16384
	ds_read_b128 v[186:189], v186 offset:20480
	s_add_i32 m0, s18, 0x4000
	s_add_u32 s100, s72, 0x21206000
	s_addc_u32 s101, s73, 0
	global_load_lds_dwordx4 v174, s[100:101]
	v_exp_f32_e32 v94, v94
	s_waitcnt lgkmcnt(0)
	v_mfma_f32_32x32x16_bf16 v[96:111], v[168:171], v[116:119], v[96:111]
	v_mfma_f32_32x32x16_bf16 v[64:79], v[186:189], v[116:119], v[64:79]
	v_add_u32_e32 v186, s14, v229
	ds_read_b128 v[168:171], v186 offset:16384
	ds_read_b128 v[186:189], v186 offset:20480
	v_exp_f32_e32 v95, v95
	s_waitcnt lgkmcnt(0)
	v_mfma_f32_32x32x16_bf16 v[96:111], v[168:171], v[112:115], v[96:111]
	v_exp_f32_e32 v168, v80
	v_add_f32_e32 v80, 0, v172
	v_add_f32_e32 v80, v173, v80
	v_add_f32_e32 v80, v182, v80
	v_add_f32_e32 v80, v195, v80
	v_add_f32_e32 v80, v196, v80
	v_add_f32_e32 v80, v197, v80
	v_add_f32_e32 v80, v198, v80
	v_add_f32_e32 v80, v199, v80
	v_add_f32_e32 v80, v200, v80
	v_add_f32_e32 v80, v234, v80
	v_add_f32_e32 v80, v235, v80
	v_add_f32_e32 v80, v236, v80
	v_add_f32_e32 v80, v237, v80
	v_exp_f32_e32 v169, v81
	v_add_f32_e32 v80, v238, v80
	v_exp_f32_e32 v170, v82
	v_add_f32_e32 v80, v239, v80
	v_exp_f32_e32 v171, v83
	v_add_f32_e32 v80, v240, v80
	v_mfma_f32_32x32x16_bf16 v[64:79], v[186:189], v[112:115], v[64:79]
	v_exp_f32_e32 v186, v84
	v_add_f32_e32 v80, v168, v80
	v_exp_f32_e32 v187, v85
	v_add_f32_e32 v80, v169, v80
	v_exp_f32_e32 v188, v86
	v_add_f32_e32 v80, v170, v80
	v_exp_f32_e32 v189, v87
	v_add_f32_e32 v80, v171, v80
	v_add_f32_e32 v80, v186, v80
	v_add_f32_e32 v80, v187, v80
	v_add_f32_e32 v80, v188, v80
	v_add_f32_e32 v80, v189, v80
	v_add_f32_e32 v80, v190, v80
	v_add_f32_e32 v80, v191, v80
	v_add_f32_e32 v80, v192, v80
	v_add_f32_e32 v80, v193, v80
	v_add_f32_e32 v80, v241, v80
	v_add_f32_e32 v80, v242, v80
	v_add_f32_e32 v80, v94, v80
	v_add_f32_e32 v80, v95, v80
	v_mov_b32_e32 v81, v80
	v_cvt_pk_bf16_f32 v82, v172, v173
	v_cvt_pk_bf16_f32 v83, v182, v195
	v_cvt_pk_bf16_f32 v84, v196, v197
	s_nop 1
	v_permlane32_swap_b32_e32 v80, v81
	v_cvt_pk_bf16_f32 v85, v198, v199
	v_permlane32_swap_b32_e32 v82, v84
	v_cvt_pk_bf16_f32 v86, v200, v234
	v_cvt_pk_bf16_f32 v87, v235, v236
	v_cvt_pk_bf16_f32 v88, v237, v238
	v_cvt_pk_bf16_f32 v89, v239, v240
	v_cvt_pk_bf16_f32 v90, v168, v169
	v_cvt_pk_bf16_f32 v91, v170, v171
	v_cvt_pk_bf16_f32 v92, v186, v187
	v_cvt_pk_bf16_f32 v93, v188, v189
	v_cvt_pk_bf16_f32 v168, v190, v191
	v_cvt_pk_bf16_f32 v169, v192, v193
	v_cvt_pk_bf16_f32 v170, v241, v242
	v_cvt_pk_bf16_f32 v171, v94, v95
	v_lshl_add_u32 v94, s13, 14, v205
	ds_read_b64_tr_b16 v[186:187], v94 offset:0
	ds_read_b64_tr_b16 v[188:189], v94 offset:0x800
	ds_read_b64_tr_b16 v[190:191], v94 offset:0x1000
	ds_read_b64_tr_b16 v[192:193], v94 offset:0x1800
	ds_read_b64_tr_b16 v[196:197], v94 offset:0x2000
	ds_read_b64_tr_b16 v[198:199], v94 offset:0x2800
	ds_read_b64_tr_b16 v[234:235], v94 offset:0x3000
	ds_read_b64_tr_b16 v[236:237], v94 offset:0x3800
	v_permlane32_swap_b32_e32 v83, v85
	v_permlane32_swap_b32_e32 v86, v88
	v_permlane32_swap_b32_e32 v87, v89
	v_permlane32_swap_b32_e32 v90, v92
	v_permlane32_swap_b32_e32 v91, v93
	v_permlane32_swap_b32_e32 v168, v170
	v_permlane32_swap_b32_e32 v169, v171
	s_setprio 0
	s_waitcnt lgkmcnt(0)
; #define SBAR() __builtin_amdgcn_sched_barrier(0)
; template <bool FIRST>
; __device__ __forceinline__ void partialSM(f32x16& p0, f32x16& p1, float& m_reg, float& mn, float& alpha) {
;     float pmax = p0[0];
; #pragma unroll
;     for (int r = 1; r < 16; ++r) pmax = fmaxf(pmax, p0[r]);
; #pragma unroll
;     for (int r = 0; r < 16; ++r) pmax = fmaxf(pmax, p1[r]);
;     { auto rr = __builtin_amdgcn_permlane32_swap(__float_as_uint(pmax), __float_as_uint(pmax), false, false);
;       pmax = fmaxf(__uint_as_float(rr[0]), __uint_as_float(rr[1])); }
;     if (FIRST) { mn = (fabsf(pmax) <= THRL) ? 0.f : pmax; m_reg = mn; alpha = 1.f; }
;     else if (__builtin_expect(__all(pmax - m_reg <= THRL), 1)) { mn = m_reg; alpha = 1.f; }
;     else { mn = fmaxf(m_reg, pmax); alpha = __builtin_amdgcn_exp2f(m_reg - mn); m_reg = mn; }
; template <int OFF> __device__ __forceinline__ s16x4 tr_read(int vb) {
;     s16x4 r; asm volatile("ds_read_b64_tr_b16 %0, %1 offset:%2" : "=&v"(r) : "v"(vb), "i"(OFF) : "memory"); return r;
; }
; template <int D0> __device__ __forceinline__ void pv_one(f32x16& od, int vb, bf16x8 pa0, bf16x8 pa1, bf16x8 pa2, bf16x8 pa3) {
;     const s16x4 l0 = tr_read<v_rd_off(D0, 0, 0)>(vb), h0 = tr_read<v_rd_off(D0, 0, 1)>(vb), l1 = tr_read<v_rd_off(D0, 1, 0)>(vb), h1 = tr_read<v_rd_off(D0, 1, 1)>(vb);
;     const s16x4 l2 = tr_read<v_rd_off(D0, 2, 0)>(vb), h2 = tr_read<v_rd_off(D0, 2, 1)>(vb), l3 = tr_read<v_rd_off(D0, 3, 0)>(vb), h3 = tr_read<v_rd_off(D0, 3, 1)>(vb);
;     asm volatile("s_waitcnt lgkmcnt(0)" ::: "memory"); SBAR();
;     ...
;     od = __builtin_amdgcn_mfma_f32_32x32x16_bf16(pa0, PK(l0, h0), od, 0, 0, 0);
;     od = __builtin_amdgcn_mfma_f32_32x32x16_bf16(pa1, PK(l1, h1), od, 0, 0, 0);
;     od = __builtin_amdgcn_mfma_f32_32x32x16_bf16(pa2, PK(l2, h2), od, 0, 0, 0);
;     od = __builtin_amdgcn_mfma_f32_32x32x16_bf16(pa3, PK(l3, h3), od, 0, 0, 0);
;     ...
; }
; __device__ __forceinline__ void pv_d0(f32x16* o, int vb, bf16x8 pa0, bf16x8 pa1, bf16x8 pa2, bf16x8 pa3) {
;     pv_one<0>(o[0], vb, pa0, pa1, pa2, pa3); pv_one<1>(o[1], vb, pa0, pa1, pa2, pa3); pv_one<2>(o[2], vb, pa0, pa1, pa2, pa3); pv_one<3>(o[3], vb, pa0, pa1, pa2, pa3);
	s_nop 0
	v_mfma_f32_32x32x16_bf16 v[0:15], v[82:85], v[186:189], v[0:15]
	ds_read_b64_tr_b16 v[186:187], v94 offset:0x200
	ds_read_b64_tr_b16 v[188:189], v94 offset:0xa00
	v_mfma_f32_32x32x16_bf16 v[0:15], v[86:89], v[190:193], v[0:15]
	ds_read_b64_tr_b16 v[190:191], v94 offset:0x1200
	ds_read_b64_tr_b16 v[192:193], v94 offset:0x1a00
	v_mfma_f32_32x32x16_bf16 v[0:15], v[90:93], v[196:199], v[0:15]
	ds_read_b64_tr_b16 v[196:197], v94 offset:0x2200
	ds_read_b64_tr_b16 v[198:199], v94 offset:0x2a00
	v_mfma_f32_32x32x16_bf16 v[0:15], v[168:171], v[234:237], v[0:15]
	ds_read_b64_tr_b16 v[234:235], v94 offset:0x3200
	ds_read_b64_tr_b16 v[236:237], v94 offset:0x3a00
	s_waitcnt lgkmcnt(0)
	v_mfma_f32_32x32x16_bf16 v[48:63], v[82:85], v[186:189], v[48:63]
	ds_read_b64_tr_b16 v[186:187], v94 offset:0x400
	ds_read_b64_tr_b16 v[188:189], v94 offset:0xc00
	v_mfma_f32_32x32x16_bf16 v[48:63], v[86:89], v[190:193], v[48:63]
	ds_read_b64_tr_b16 v[190:191], v94 offset:0x1400
	ds_read_b64_tr_b16 v[192:193], v94 offset:0x1c00
	v_mfma_f32_32x32x16_bf16 v[48:63], v[90:93], v[196:199], v[48:63]
	ds_read_b64_tr_b16 v[196:197], v94 offset:0x2400
	ds_read_b64_tr_b16 v[198:199], v94 offset:0x2c00
	v_mfma_f32_32x32x16_bf16 v[48:63], v[168:171], v[234:237], v[48:63]
	ds_read_b64_tr_b16 v[234:235], v94 offset:0x3400
	ds_read_b64_tr_b16 v[236:237], v94 offset:0x3c00
	s_waitcnt lgkmcnt(0)
	v_mfma_f32_32x32x16_bf16 v[32:47], v[82:85], v[186:189], v[32:47]
	ds_read_b64_tr_b16 v[186:187], v94 offset:0x600
	ds_read_b64_tr_b16 v[188:189], v94 offset:0xe00
	v_mfma_f32_32x32x16_bf16 v[32:47], v[86:89], v[190:193], v[32:47]
	ds_read_b64_tr_b16 v[190:191], v94 offset:0x1600
	ds_read_b64_tr_b16 v[192:193], v94 offset:0x1e00
	v_mfma_f32_32x32x16_bf16 v[32:47], v[90:93], v[196:199], v[32:47]
	ds_read_b64_tr_b16 v[196:197], v94 offset:0x2600
	ds_read_b64_tr_b16 v[198:199], v94 offset:0x2e00
	v_mfma_f32_32x32x16_bf16 v[32:47], v[168:171], v[234:237], v[32:47]
	ds_read_b64_tr_b16 v[234:235], v94 offset:0x3600
	ds_read_b64_tr_b16 v[236:237], v94 offset:0x3e00
	s_waitcnt lgkmcnt(0)
	v_mfma_f32_32x32x16_bf16 v[16:31], v[82:85], v[186:189], v[16:31]
	v_max_f32_e32 v82, v97, v97
	v_max_f32_e32 v83, v96, v96
	v_max_f32_e32 v82, v83, v82
	v_max3_f32 v82, v82, v98, v99
	v_max3_f32 v82, v82, v100, v101
	v_max3_f32 v82, v82, v102, v103
	v_max3_f32 v82, v82, v104, v105
	v_mfma_f32_32x32x16_bf16 v[16:31], v[86:89], v[190:193], v[16:31]
	v_max3_f32 v82, v82, v106, v107
	v_max3_f32 v82, v82, v108, v109
	v_max3_f32 v82, v82, v110, v111
	v_max3_f32 v82, v82, v64, v65
	v_max3_f32 v82, v82, v66, v67
	v_max3_f32 v82, v82, v68, v69
	v_max3_f32 v82, v82, v70, v71
	v_mfma_f32_32x32x16_bf16 v[16:31], v[90:93], v[196:199], v[16:31]
	v_max3_f32 v82, v82, v72, v73
	v_max3_f32 v82, v82, v74, v75
	v_max3_f32 v82, v82, v76, v77
	v_max3_f32 v82, v82, v78, v79
	v_mov_b32_e32 v83, v82
	s_nop 1
	v_permlane32_swap_b32_e32 v82, v83
	v_max_f32_e32 v83, v83, v83
	v_max_f32_e32 v82, v82, v82
	v_mfma_f32_32x32x16_bf16 v[16:31], v[168:171], v[234:237], v[16:31]
	v_max_f32_e32 v82, v82, v83
	v_sub_f32_e32 v83, v82, v184
	s_mov_b32 s0, 0x41300000
	v_cmp_ge_f32_e32 vcc, s0, v83
	v_mov_b32_e32 v182, v184
	s_cmp_eq_u64 vcc, exec
	s_cbranch_scc0 .Latt_slow2
	s_cmp_lg_u32 s19, 0
	s_cbranch_scc0 .LBB0_229
	v_mov_b32_e32 v184, 1.0
